# final-rows loop: the two rows' wave-sum butterfly chains interleaved (same operations per chain)
# speedup vs baseline: 1.0049x; 1.0049x over previous
; DEVQ float wave_sum(float v) {
; #pragma unroll
;     for (int o = 1; o < 64; o <<= 1) v += __shfl_xor(v, o);
;     return v;
; }
; DEVQ void final_rows(float* out, const float* H, const float* gfin, int first, int end, int stride, int lane) {
;     for (int ro = first; ro < end; ro += stride) {
;         int m; if (ro < NBP * SEQP) { m = (ro >> 12) * LP + 16 + (ro & 4095); } else { const int r2 = ro - NBP * SEQP; m = TP + (r2 >> 13) * LS + 16 + (r2 & 8191); }
;         const RowV ra = row_load(H + (size_t)m * D, lane), rb = row_load(H + (size_t)(m + 1) * D, lane);
;         float* dst = out + (size_t)ro * D;
;         const float rsa = 1.0f / sqrtf(wave_sum(ra.ss) * (1.0f / D) + RMS_EPS), rsb = 1.0f / sqrtf(wave_sum(rb.ss) * (1.0f / D) + RMS_EPS);
; #pragma unroll
;         for (int j = 0; j < 4; ++j) { const f32x4 gv = ((const f32x4*)gfin)[lane + 64 * j]; ((f32x4*)dst)[lane + 64 * j] = ra.v[j] * rsa * gv; ((f32x4*)(dst + D))[lane + 64 * j] = rb.v[j] * rsb * gv; }
;     }
.LBB0_18:
	s_and_b32 s1, s1, s6
	s_add_i32 s0, s1, s0
	s_add_i32 s0, s0, s2
	s_ashr_i32 s1, s0, 31
	s_lshl_b64 s[2:3], s[0:1], 12
	v_lshl_add_u64 v[0:1], v[38:39], 0, s[2:3]
	flat_load_dwordx4 v[12:15], v[0:1]
	flat_load_dwordx4 v[8:11], v[0:1] offset:1024
	flat_load_dwordx4 v[4:7], v[0:1] offset:2048
	s_nop 0
	flat_load_dwordx4 v[0:3], v[0:1] offset:3072
	s_or_b32 s0, s0, 1
	s_ashr_i32 s1, s0, 31
	s_lshl_b64 s[0:1], s[0:1], 12
	s_add_i32 s6, s6, s8
	s_cmp_lt_i32 s6, 0x14000
	s_waitcnt vmcnt(0) lgkmcnt(0)
	v_pk_mul_f32 v[16:17], v[14:15], v[14:15]
	v_pk_mul_f32 v[18:19], v[12:13], v[12:13]
	s_nop 0
	v_pk_mov_b32 v[20:21], v[18:19], v[16:17] op_sel:[1,0]
	v_mov_b32_e32 v19, v17
	v_pk_add_f32 v[16:17], v[20:21], v[18:19]
	v_pk_mul_f32 v[18:19], v[10:11], v[10:11]
	v_pk_mul_f32 v[20:21], v[8:9], v[8:9]
	v_pk_add_f32 v[16:17], v[16:17], v[16:17] op_sel:[0,1] op_sel_hi:[1,0]
	v_pk_mov_b32 v[22:23], v[20:21], v[18:19] op_sel:[1,0]
	v_mov_b32_e32 v21, v19
	v_pk_add_f32 v[18:19], v[22:23], v[20:21]
	v_mul_f32_e32 v20, v0, v0
	v_mul_f32_e32 v21, v1, v1
	v_pk_add_f32 v[18:19], v[18:19], v[18:19] op_sel:[0,1] op_sel_hi:[1,0]
	v_mov_b32_e32 v17, v20
	v_mov_b32_e32 v19, v21
	v_pk_add_f32 v[16:17], v[16:17], v[18:19]
	v_mul_f32_e32 v18, v5, v5
	v_mul_f32_e32 v20, v7, v7
	v_mul_f32_e32 v22, v2, v2
	v_mul_f32_e32 v23, v3, v3
	v_pk_fma_f32 v[18:19], v[4:5], v[4:5], v[18:19] op_sel_hi:[1,1,0]
	v_pk_fma_f32 v[20:21], v[6:7], v[6:7], v[20:21] op_sel_hi:[1,1,0]
	v_mov_b32_e32 v19, v22
	v_mov_b32_e32 v21, v23
	v_pk_add_f32 v[18:19], v[18:19], v[20:21]
	s_nop 0
	v_pk_add_f32 v[16:17], v[16:17], v[18:19]
	s_nop 0
	v_add_f32_e32 v44, v16, v17
	v_lshl_add_u64 v[16:17], v[38:39], 0, s[0:1]
	flat_load_dwordx4 v[28:31], v[16:17]
	flat_load_dwordx4 v[24:27], v[16:17] offset:1024
	flat_load_dwordx4 v[20:23], v[16:17] offset:2048
	s_nop 0
	flat_load_dwordx4 v[16:19], v[16:17] offset:3072
	s_waitcnt vmcnt(0) lgkmcnt(0)
	v_pk_mul_f32 v[32:33], v[30:31], v[30:31]
	v_pk_mul_f32 v[34:35], v[28:29], v[28:29]
	v_mul_f32_e32 v42, v16, v16
	v_pk_mov_b32 v[50:51], v[34:35], v[32:33] op_sel:[1,0]
	v_mov_b32_e32 v35, v33
	v_pk_add_f32 v[32:33], v[50:51], v[34:35]
	v_pk_mul_f32 v[34:35], v[26:27], v[26:27]
	v_pk_mul_f32 v[50:51], v[24:25], v[24:25]
	v_pk_add_f32 v[32:33], v[32:33], v[32:33] op_sel:[0,1] op_sel_hi:[1,0]
	v_pk_mov_b32 v[52:53], v[50:51], v[34:35] op_sel:[1,0]
	v_mov_b32_e32 v51, v35
	v_pk_add_f32 v[34:35], v[52:53], v[50:51]
	v_mul_f32_e32 v50, v17, v17
	v_pk_add_f32 v[34:35], v[34:35], v[34:35] op_sel:[0,1] op_sel_hi:[1,0]
	v_mov_b32_e32 v33, v42
	v_mov_b32_e32 v35, v50
	v_pk_add_f32 v[32:33], v[32:33], v[34:35]
	v_mul_f32_e32 v34, v21, v21
	v_mul_f32_e32 v51, v18, v18
	v_pk_fma_f32 v[34:35], v[20:21], v[20:21], v[34:35] op_sel_hi:[1,1,0]
	v_mul_f32_e32 v42, v23, v23
	v_mul_f32_e32 v52, v19, v19
	v_mov_b32_e32 v35, v51
	v_pk_fma_f32 v[50:51], v[22:23], v[22:23], v[42:43] op_sel_hi:[1,1,0]
	s_nop 0
	v_mov_b32_e32 v51, v52
	v_pk_add_f32 v[34:35], v[34:35], v[50:51]
	s_nop 0
	v_pk_add_f32 v[32:33], v[32:33], v[34:35]
	s_nop 0
	v_add_f32_e32 v32, v32, v33
	ds_bpermute_b32 v33, v43, v44
	ds_bpermute_b32 v97, v43, v32
	s_waitcnt lgkmcnt(0)
	v_add_f32_e32 v33, v44, v33
	v_add_f32_e32 v96, v32, v97
	ds_bpermute_b32 v34, v45, v33
	ds_bpermute_b32 v97, v45, v96
	s_waitcnt lgkmcnt(0)
	v_add_f32_e32 v33, v33, v34
	v_add_f32_e32 v96, v96, v97
	ds_bpermute_b32 v34, v46, v33
	ds_bpermute_b32 v97, v46, v96
	s_waitcnt lgkmcnt(0)
	v_add_f32_e32 v33, v33, v34
	v_add_f32_e32 v96, v96, v97
	ds_bpermute_b32 v34, v47, v33
	ds_bpermute_b32 v97, v47, v96
	s_waitcnt lgkmcnt(0)
	v_add_f32_e32 v33, v33, v34
	v_add_f32_e32 v96, v96, v97
	ds_bpermute_b32 v34, v48, v33
	ds_bpermute_b32 v97, v48, v96
	s_waitcnt lgkmcnt(0)
	v_add_f32_e32 v33, v33, v34
	v_add_f32_e32 v96, v96, v97
	ds_bpermute_b32 v34, v49, v33
	ds_bpermute_b32 v97, v49, v96
	s_waitcnt lgkmcnt(0)
; DEVQ void final_rows(float* out, const float* H, const float* gfin, int first, int end, int stride, int lane) {
;     ...
;         const float rsa = 1.0f / sqrtf(wave_sum(ra.ss) * (1.0f / D) + RMS_EPS), rsb = 1.0f / sqrtf(wave_sum(rb.ss) * (1.0f / D) + RMS_EPS);
; #pragma unroll
;         for (int j = 0; j < 4; ++j) { const f32x4 gv = ((const f32x4*)gfin)[lane + 64 * j]; ((f32x4*)dst)[lane + 64 * j] = ra.v[j] * rsa * gv; ((f32x4*)(dst + D))[lane + 64 * j] = rb.v[j] * rsb * gv; }
	v_add_f32_e32 v33, v33, v34
	v_add_f32_e32 v96, v96, v97
	v_fmamk_f32 v33, v33, 0x3a800000, v178
	v_cmp_gt_f32_e32 vcc, s7, v33
	v_mul_f32_e32 v34, 0x4f800000, v33
	s_nop 0
	v_cndmask_b32_e32 v33, v33, v34, vcc
	v_sqrt_f32_e32 v34, v33
	s_nop 0
	v_add_u32_e32 v35, -1, v34
	v_fma_f32 v42, -v35, v34, v33
	v_cmp_ge_f32_e64 s[0:1], 0, v42
	v_add_u32_e32 v42, 1, v34
	s_nop 0
	v_cndmask_b32_e64 v35, v34, v35, s[0:1]
	v_fma_f32 v34, -v42, v34, v33
	v_cmp_lt_f32_e64 s[0:1], 0, v34
	s_nop 1
	v_cndmask_b32_e64 v34, v35, v42, s[0:1]
	v_mul_f32_e32 v35, 0x37800000, v34
	v_cndmask_b32_e32 v34, v34, v35, vcc
	v_cmp_class_f32_e32 vcc, v33, v179
	s_nop 1
	v_cndmask_b32_e32 v33, v34, v33, vcc
	v_div_scale_f32 v34, s[0:1], v33, v33, 1.0
	v_rcp_f32_e32 v35, v34
	s_nop 0
	v_fma_f32 v42, -v34, v35, 1.0
	v_fmac_f32_e32 v35, v42, v35
	v_div_scale_f32 v42, vcc, 1.0, v33, 1.0
	v_mul_f32_e32 v44, v42, v35
	v_fma_f32 v50, -v34, v44, v42
	v_fmac_f32_e32 v44, v50, v35
	v_fma_f32 v34, -v34, v44, v42
	v_div_fmas_f32 v34, v34, v35, v44
	v_div_fixup_f32 v42, v34, v33, 1.0
	v_mov_b32_e32 v32, v96
	v_pk_mul_f32 v[12:13], v[12:13], v[42:43] op_sel_hi:[1,0]
	v_pk_mul_f32 v[14:15], v[14:15], v[42:43] op_sel_hi:[1,0]
	v_pk_mul_f32 v[10:11], v[10:11], v[42:43] op_sel_hi:[1,0]
	v_pk_mul_f32 v[8:9], v[8:9], v[42:43] op_sel_hi:[1,0]
	v_pk_mul_f32 v[6:7], v[6:7], v[42:43] op_sel_hi:[1,0]
	v_pk_mul_f32 v[4:5], v[4:5], v[42:43] op_sel_hi:[1,0]
	v_pk_mul_f32 v[2:3], v[2:3], v[42:43] op_sel_hi:[1,0]
	v_pk_mul_f32 v[0:1], v[0:1], v[42:43] op_sel_hi:[1,0]
	v_fmamk_f32 v32, v32, 0x3a800000, v178
	v_cmp_gt_f32_e32 vcc, s7, v32
	v_mul_f32_e32 v33, 0x4f800000, v32
	s_nop 0
	v_cndmask_b32_e32 v32, v32, v33, vcc
	v_sqrt_f32_e32 v33, v32
	s_nop 0
	v_add_u32_e32 v34, -1, v33
	v_fma_f32 v35, -v34, v33, v32
	v_cmp_ge_f32_e64 s[0:1], 0, v35
	v_add_u32_e32 v35, 1, v33
	s_nop 0
	v_cndmask_b32_e64 v34, v33, v34, s[0:1]
	v_fma_f32 v33, -v35, v33, v32
	v_cmp_lt_f32_e64 s[0:1], 0, v33
	s_nop 1
	v_cndmask_b32_e64 v33, v34, v35, s[0:1]
	v_mul_f32_e32 v34, 0x37800000, v33
	v_cndmask_b32_e32 v33, v33, v34, vcc
	v_cmp_class_f32_e32 vcc, v32, v179
	s_nop 1
	v_cndmask_b32_e32 v32, v33, v32, vcc
	v_div_scale_f32 v33, s[0:1], v32, v32, 1.0
	v_rcp_f32_e32 v34, v33
	s_nop 0
	v_fma_f32 v35, -v33, v34, 1.0
	v_fmac_f32_e32 v34, v35, v34
	v_div_scale_f32 v35, vcc, 1.0, v32, 1.0
	v_mul_f32_e32 v44, v35, v34
	v_fma_f32 v50, -v33, v44, v35
	v_fmac_f32_e32 v44, v50, v34
	v_fma_f32 v33, -v33, v44, v35
	v_div_fmas_f32 v33, v33, v34, v44
	v_div_fixup_f32 v44, v33, v32, 1.0
	flat_load_dwordx4 v[32:35], v[36:37]
	s_waitcnt vmcnt(0) lgkmcnt(0)
	v_pk_mul_f32 v[14:15], v[34:35], v[14:15]
	v_pk_mul_f32 v[12:13], v[32:33], v[12:13]
	flat_store_dwordx4 v[40:41], v[12:15]
	s_nop 1
	v_pk_mul_f32 v[12:13], v[28:29], v[44:45] op_sel_hi:[1,0]
	v_pk_mul_f32 v[14:15], v[30:31], v[44:45] op_sel_hi:[1,0]
	v_add_co_u32_e32 v28, vcc, s50, v40
	v_pk_mul_f32 v[14:15], v[34:35], v[14:15]
	v_pk_mul_f32 v[12:13], v[32:33], v[12:13]
	v_addc_co_u32_e32 v29, vcc, 0, v41, vcc
	flat_store_dwordx4 v[28:29], v[12:15]
	flat_load_dwordx4 v[12:15], v[36:37] offset:1024
	s_waitcnt vmcnt(0) lgkmcnt(0)
	v_pk_mul_f32 v[8:9], v[8:9], v[12:13]
	v_pk_mul_f32 v[10:11], v[10:11], v[14:15]
	flat_store_dwordx4 v[40:41], v[8:11] offset:1024
	s_nop 1
	v_pk_mul_f32 v[10:11], v[26:27], v[44:45] op_sel_hi:[1,0]
	v_pk_mul_f32 v[8:9], v[24:25], v[44:45] op_sel_hi:[1,0]
	v_pk_mul_f32 v[10:11], v[14:15], v[10:11]
	v_pk_mul_f32 v[8:9], v[12:13], v[8:9]
	flat_store_dwordx4 v[28:29], v[8:11] offset:1024
	flat_load_dwordx4 v[8:11], v[36:37] offset:2048
	s_waitcnt vmcnt(0) lgkmcnt(0)
	v_pk_mul_f32 v[4:5], v[4:5], v[8:9]
	v_pk_mul_f32 v[6:7], v[6:7], v[10:11]
	flat_store_dwordx4 v[40:41], v[4:7] offset:2048
	s_nop 1
	v_pk_mul_f32 v[6:7], v[22:23], v[44:45] op_sel_hi:[1,0]
	v_pk_mul_f32 v[4:5], v[20:21], v[44:45] op_sel_hi:[1,0]
	v_pk_mul_f32 v[6:7], v[10:11], v[6:7]
	v_pk_mul_f32 v[4:5], v[8:9], v[4:5]
	flat_store_dwordx4 v[28:29], v[4:7] offset:2048
	flat_load_dwordx4 v[4:7], v[36:37] offset:3072
	s_waitcnt vmcnt(0) lgkmcnt(0)
	v_pk_mul_f32 v[0:1], v[0:1], v[4:5]
	v_pk_mul_f32 v[2:3], v[2:3], v[6:7]
	flat_store_dwordx4 v[40:41], v[0:3] offset:3072
	v_lshl_add_u64 v[40:41], v[40:41], 0, s[10:11]
	s_nop 0
	v_pk_mul_f32 v[2:3], v[18:19], v[44:45] op_sel_hi:[1,0]
	v_pk_mul_f32 v[0:1], v[16:17], v[44:45] op_sel_hi:[1,0]
	v_pk_mul_f32 v[2:3], v[2:3], v[6:7]
	v_pk_mul_f32 v[0:1], v[0:1], v[4:5]
	flat_store_dwordx4 v[28:29], v[0:3] offset:3072
	s_cbranch_scc0 .LBB0_23
